# SSD2 cross-chunk scan items remapped so each workgroup scans a contiguous 4 KB per chunk (on top of guarded plain ring stores etc.)
# baseline (speedup 1.0000x reference)
; #define RD_PEEK(cc) __hip_atomic_load(READY + bh * 512 + (cc), __ATOMIC_RELAXED, __HIP_MEMORY_SCOPE_AGENT)
; __device__ void phase_rwkv_dist(const Params& p, LAS unsigned char* lds, int wg, int nwg) {
;     ...
;             bf16_t* SS = (bf16_t*)p.out; const float* CD = (const float*)(p.ws + WS_CTL + WS_CD);
;             const int nitem = (BATCH * 32 * 64 * 32 + nwg * 64 - 1) / (nwg * 64), nstep = ((nitem + 3) / 4) * 128;
;             const int per = (nitem + 3) / 4;
;             int s2 = (unit == wg) ? 0 : nstep; f32x4 hh = zero4;
;             RD_ISSUE(fw, 0, 0u);
;             for (int c2 = fw; c2 < RC_NCHK; c2 += 8) {
;                 const unsigned pr1 = RD_PEEK(c2 + 4), pr0 = (c2 + 8 < RC_NCHK) ? RD_PEEK(c2 + 8) : 0u;
;                 u32x2 raw[4]; float dd[4]; bf16_t* qq[4]; bool ok[4];
; #pragma unroll
;                 for (int k = 0; k < 4; ++k) { const int ss = s2 + k, item = fw * per + (ss >> 7), cc = ss & 127, idx = item * (nwg * 64) + wg * 64 + lane; ok[k] = ss < nstep && (ss >> 7) < per && item < nitem && idx < BATCH * 32 * 64 * 32;
;                     const int n4 = idx & 31, pp = (idx >> 5) & 63, eg = (idx >> 11) & 31, bb = idx >> 16;
;                     qq[k] = SS + ((((size_t)bb * 128 + cc) * 32 + eg) * 64 + pp) * 128 + 4 * n4; raw[k] = (u32x2){0u, 0u}; dd[k] = 0.f;
;                     if (ok[k]) { raw[k] = *(const u32x2*)qq[k]; dd[k] = CD[(bb * 128 + cc) * 32 + eg]; } }
.LBB0_681:
	v_readlane_b32 s6, v253, 51
	s_cmp_lg_u32 s51, s6
	v_readlane_b32 s6, v254, 18
	v_readlane_b32 s7, v254, 19
	s_cselect_b32 s81, s56, 0
	s_andn2_b64 vcc, exec, s[6:7]
	s_cbranch_vccnz .LBB0_769
	v_writelane_b32 v254, s72, 46
	s_lshl_b32 s84, s94, 20
	v_readlane_b32 s6, v254, 14
	s_add_i32 s6, s80, s6
	s_add_i32 s7, s6, 0x2000
	buffer_load_dwordx4 v[80:83], v197, s[52:55], s7 offen sc1
	buffer_load_dwordx4 v[72:75], v196, s[52:55], s7 offen sc1
	s_add_i32 s7, s6, 0x1000
	buffer_load_dwordx4 v[88:91], v215, s[52:55], s7 offen sc1
	buffer_load_dwordx4 v[84:87], v213, s[52:55], s7 offen sc1
	buffer_load_dwordx4 v[96:99], v197, s[52:55], s7 offen sc1
	buffer_load_dwordx4 v[92:95], v196, s[52:55], s7 offen sc1
	buffer_load_dwordx4 v[64:67], v215, s[52:55], s6 offen sc1
	buffer_load_dwordx4 v[60:63], v213, s[52:55], s6 offen sc1
	buffer_load_dwordx4 v[68:71], v197, s[52:55], s6 offen sc1
	buffer_load_dwordx4 v[76:79], v196, s[52:55], s6 offen sc1
	v_readlane_b32 s7, v254, 16
	s_add_i32 s7, s84, s7
	s_add_i32 s16, s7, 0xdffff80
	v_or_b32_e32 v0, s40, v200
	s_cmp_gt_i32 s7, 0
	v_lshlrev_b32_e32 v157, 1, v0
	s_cselect_b32 s17, 0, 0xffffff80
	v_add_u32_e32 v0, s17, v157
	s_cselect_b32 s16, s16, 0xe000000
	s_add_i32 s7, s7, 0xe000000
	s_addk_i32 s6, 0x2800
	buffer_load_dwordx2 v[176:177], v0, s[52:55], s16 offen
	buffer_load_dwordx2 v[178:179], v157, s[52:55], s7 offen
	buffer_load_dwordx4 v[100:103], v202, s[52:55], s6 offen sc1
	v_readlane_b32 s6, v254, 0
	s_add_u32 s85, s6, s2
	v_readlane_b32 s2, v254, 2
	v_mov_b32_e32 v2, v1
	v_mov_b32_e32 v3, v1
	s_addc_u32 s86, s2, s3
	v_mov_b32_e32 v0, v1
	v_mov_b64_e32 v[58:59], v[2:3]
	v_readlane_b32 s2, v254, 42
	s_mov_b32 s95, s45
	v_mov_b64_e32 v[56:57], v[0:1]
	s_mov_b32 s72, s2
	v_readlane_b32 s3, v254, 43
	s_lshl_b32 s100, s72, 2
	s_add_u32 s100, s82, s100
	s_addc_u32 s101, s83, 0
	global_load_dword v229, v1, s[100:101] offset:16 sc1
	global_load_dword v230, v1, s[100:101] offset:32 sc1
	s_mov_b32 s99, 0
	s_mov_b32 s32, 0
	v_mov_b32_e32 v2, 0
	s_ashr_i32 s2, s81, 7
	v_readlane_b32 s3, v254, 40
	s_add_i32 s3, s2, s3
	s_lshl_b32 s16, s3, 6
	s_lshr_b32 s100, s51, 2
	s_lshl_b32 s100, s100, 11
	s_or_b32 s16, s16, s100
	s_and_b32 s100, s51, 3
	s_lshl_b32 s100, s100, 9
	s_or_b32 s16, s16, s100
	s_cmp_lt_i32 s2, s48
	s_cselect_b64 s[46:47], -1, 0
	s_cmp_lt_i32 s3, s20
	s_cselect_b64 s[60:61], -1, 0
	s_ashr_i32 s2, s16, 16
	s_ashr_i32 s3, s2, 31
	s_bfe_u32 s17, s16, 0x5000b
	s_lshl_b64 s[18:19], s[2:3], 12
	s_lshl_b32 s2, s2, 12
	s_or_b32 s88, s18, s17
	s_or_b32 s87, s2, s17
	s_cmp_lt_i32 s81, s56
	s_cselect_b64 s[2:3], -1, 0
	v_or_b32_e32 v0, s16, v165
	s_and_b64 s[2:3], s[2:3], s[46:47]
	v_cmp_gt_i32_e32 vcc, s55, v0
	s_and_b64 s[2:3], s[2:3], s[60:61]
	s_and_b64 s[58:59], s[2:3], vcc
	s_lshl_b32 s2, s81, 5
	v_lshlrev_b32_e32 v0, 3, v0
	s_and_b32 s16, s2, 0xf80
	v_and_b32_e32 v0, 0x3f00, v0
	s_or_b32 s18, s88, s16
	v_lshl_add_u64 v[104:105], v[154:155], 0, v[0:1]
	s_lshl_b64 s[2:3], s[18:19], 14
	v_lshl_add_u64 v[158:159], v[104:105], 0, s[2:3]
	v_mov_b32_e32 v162, 0
	v_mov_b32_e32 v163, 0
	s_and_saveexec_b64 s[2:3], s[58:59]
	s_cbranch_execz .Lssd2p_687
	s_add_i32 s32, s32, 2
	s_or_b32 s16, s87, s16
	s_ashr_i32 s17, s16, 31
	s_lshl_b64 s[16:17], s[16:17], 2
	v_readlane_b32 s62, v253, 54
	v_readlane_b32 s63, v253, 55
	s_add_u32 s16, s62, s16
	s_addc_u32 s17, s63, s17
	global_load_dwordx2 v[162:163], v[158:159], off
	global_load_dword v2, v1, s[16:17]

; __device__ void phase_rwkv_dist(const Params& p, LAS unsigned char* lds, int wg, int nwg) {
;     ...
;                 u32x2 raw[4]; float dd[4]; bf16_t* qq[4]; bool ok[4];
; #pragma unroll
;                 for (int k = 0; k < 4; ++k) { const int ss = s2 + k, item = fw * per + (ss >> 7), cc = ss & 127, idx = item * (nwg * 64) + wg * 64 + lane; ok[k] = ss < nstep && (ss >> 7) < per && item < nitem && idx < BATCH * 32 * 64 * 32;
;                     const int n4 = idx & 31, pp = (idx >> 5) & 63, eg = (idx >> 11) & 31, bb = idx >> 16;
;                     qq[k] = SS + ((((size_t)bb * 128 + cc) * 32 + eg) * 64 + pp) * 128 + 4 * n4; raw[k] = (u32x2){0u, 0u}; dd[k] = 0.f;
;                     if (ok[k]) { raw[k] = *(const u32x2*)qq[k]; dd[k] = CD[(bb * 128 + cc) * 32 + eg]; } }
.LBB0_768:
	s_mov_b32 s32, 0
	v_mov_b32_e32 v2, 0
	s_ashr_i32 s2, s81, 7
	v_readlane_b32 s3, v254, 40
	s_add_i32 s3, s2, s3
	s_lshl_b32 s16, s3, 6
	s_lshr_b32 s100, s51, 2
	s_lshl_b32 s100, s100, 11
	s_or_b32 s16, s16, s100
	s_and_b32 s100, s51, 3
	s_lshl_b32 s100, s100, 9
	s_or_b32 s16, s16, s100
	s_cmp_lt_i32 s2, s48
	s_cselect_b64 s[46:47], -1, 0
	s_cmp_lt_i32 s3, s20
	s_cselect_b64 s[60:61], -1, 0
	s_ashr_i32 s2, s16, 16
	s_ashr_i32 s3, s2, 31
	s_bfe_u32 s17, s16, 0x5000b
	s_lshl_b64 s[18:19], s[2:3], 12
	s_lshl_b32 s2, s2, 12
	s_or_b32 s88, s18, s17
	s_or_b32 s87, s2, s17
	s_cmp_lt_i32 s81, s56
	s_cselect_b64 s[2:3], -1, 0
	v_or_b32_e32 v0, s16, v165
	s_and_b64 s[2:3], s[2:3], s[46:47]
	v_cmp_gt_i32_e32 vcc, s55, v0
	s_and_b64 s[2:3], s[2:3], s[60:61]
	s_and_b64 s[58:59], s[2:3], vcc
	s_lshl_b32 s2, s81, 5
	v_lshlrev_b32_e32 v0, 3, v0
	s_and_b32 s16, s2, 0xf80
	v_and_b32_e32 v0, 0x3f00, v0
	s_or_b32 s18, s88, s16
	v_lshl_add_u64 v[104:105], v[154:155], 0, v[0:1]
	s_lshl_b64 s[2:3], s[18:19], 14
	v_lshl_add_u64 v[158:159], v[104:105], 0, s[2:3]
	v_mov_b32_e32 v162, 0
	v_mov_b32_e32 v163, 0
	s_and_saveexec_b64 s[2:3], s[58:59]
	s_cbranch_execz .LBB0_687
	s_add_i32 s32, s32, 2
	s_or_b32 s16, s87, s16
	s_ashr_i32 s17, s16, 31
	s_lshl_b64 s[16:17], s[16:17], 2
	v_readlane_b32 s62, v253, 54
	v_readlane_b32 s63, v253, 55
	s_add_u32 s16, s62, s16
	s_addc_u32 s17, s63, s17
	global_load_dwordx2 v[162:163], v[158:159], off
	global_load_dword v2, v1, s[16:17]
